# v67 plus static s_setprio 1 for waves 4-7 over the whole attention phase (reset at phase end)
# speedup vs baseline: 1.0007x; 1.0007x over previous
.LBB0_198:
	s_setprio 0
	v_readlane_b32 s60, v235, 53
	v_readlane_b32 s68, v234, 10
	v_readlane_b32 s62, v235, 55
	s_mov_b64 s[28:29], 0
	v_readlane_b32 s61, v235, 54
	v_readlane_b32 s70, v234, 12
	v_readlane_b32 s71, v234, 13
	v_readlane_b32 s63, v235, 56
	v_readlane_b32 s72, v235, 59
	v_readlane_b32 s83, v235, 60
	v_readlane_b32 s73, v235, 61
	v_readlane_b32 s76, v234, 0
	v_readlane_b32 s69, v234, 11

.LBB0_204:
	v_readfirstlane_b32 vcc_lo, v200
	s_bitcmp1_b32 vcc_lo, 8
	s_cbranch_scc0 .Lap_skip
	s_setprio 1
